# cached-stream forgetting-attention units publish their split partials with write-through stores; the release fence (L2 write-back) is no longer on the unit's critical chain
# baseline (speedup 1.0000x reference)
; #define LDS_AS __attribute__((address_space(3)))
;     ...
;     {
;         const float lt = st.l + __shfl_xor(st.l, 32);
;         float* pp = p.part + ((((size_t)bb * NSPLIT + split) * 8) + wave) * PART_STRIDE;
;         if (hh == 0) { pp[l31] = st.m; pp[32 + l31] = lt; }
; #pragma unroll
;         for (int dt = 0; dt < 2; ++dt)
; #pragma unroll
;             for (int g = 0; g < 4; ++g) {
;                 const int d = 32 * dt + 8 * g + 4 * hh;
;                 const f32x16& o = dt == 0 ? st.o0 : st.o1;
;                 *(f32x4*)(pp + 64 + l31 * 64 + d) = (f32x4){o[4 * g], o[4 * g + 1], o[4 * g + 2], o[4 * g + 3]};
;             }
;     }
;     asm volatile("s_waitcnt vmcnt(0)" ::: "memory");
;     __syncthreads();
;     LDS_AS int* sflag = (LDS_AS int*)((LDS_AS char*)smem + SM_UNIT_OFF + 4);
;     if (tid == 0) {
;         __builtin_amdgcn_fence(__ATOMIC_RELEASE, "agent");
;         asm volatile("s_waitcnt vmcnt(0)" ::: "memory");
;         const unsigned old = __hip_atomic_fetch_add(p.ctrl + cq + 8 + bb, 1u, __ATOMIC_RELAXED, __HIP_MEMORY_SCOPE_AGENT);
;         const int lastf = (old == (unsigned)(NSPLIT - 1)) ? 1 : 0;
;         if (lastf) { __builtin_amdgcn_fence(__ATOMIC_ACQUIRE, "agent"); asm volatile("s_waitcnt vmcnt(0)" ::: "memory"); }
;         *sflag = lastf;
;     }
.LBB0_466:
	ds_bpermute_b32 v36, v181, v178
	s_lshl_b64 s[0:1], s[6:7], 5
	s_ashr_i32 s9, s8, 31
	v_lshl_add_u64 v[32:33], s[0:1], 0, v[136:137]
	v_lshl_add_u64 v[38:39], s[8:9], 3, v[32:33]
	v_mov_b64_e32 v[34:35], s[18:19]
	v_mad_u64_u32 v[34:35], s[0:1], v38, s94, v[34:35]
	v_mad_i32_i24 v35, v39, s94, v35
	v_cmp_gt_u32_e32 vcc, 32, v133
	s_and_saveexec_b64 s[0:1], vcc
	s_cbranch_execz .LBB0_468
	v_lshlrev_b32_e32 v130, 2, v176
	s_waitcnt lgkmcnt(0)
	v_add_f32_e32 v38, v178, v36
	v_lshl_add_u64 v[36:37], v[34:35], 0, v[130:131]
	global_store_dword v[36:37], v193, off sc0 sc1
	global_store_dword v[36:37], v38, off offset:128 sc0 sc1
.LBB0_468:
	s_or_b64 exec, exec, s[0:1]
	v_lshlrev_b32_e32 v130, 8, v176
	v_lshl_add_u64 v[34:35], v[34:35], 0, v[130:131]
	v_lshlrev_b32_e32 v130, 2, v135
	v_lshl_add_u64 v[34:35], v[34:35], 0, v[130:131]
	global_store_dwordx4 v[34:35], v[16:19], off offset:256 sc0 sc1
	global_store_dwordx4 v[34:35], v[20:23], off offset:288 sc0 sc1
	global_store_dwordx4 v[34:35], v[24:27], off offset:320 sc0 sc1
	global_store_dwordx4 v[34:35], v[28:31], off offset:352 sc0 sc1
	global_store_dwordx4 v[34:35], v[0:3], off offset:384 sc0 sc1
	global_store_dwordx4 v[34:35], v[4:7], off offset:416 sc0 sc1
	global_store_dwordx4 v[34:35], v[8:11], off offset:448 sc0 sc1
	global_store_dwordx4 v[34:35], v[12:15], off offset:480 sc0 sc1
	s_waitcnt vmcnt(0)
	v_cmp_eq_u32_e32 vcc, 0, v134
	s_waitcnt lgkmcnt(0)
	s_barrier
	s_and_saveexec_b64 s[0:1], vcc
	s_cbranch_execz .LBB0_474
	s_mov_b64 s[8:9], exec
	s_nop 0
	s_waitcnt vmcnt(0)
	s_waitcnt vmcnt(0)
	v_mbcnt_lo_u32_b32 v0, s8, 0
	v_mbcnt_hi_u32_b32 v0, s9, v0
	v_cmp_eq_u32_e32 vcc, 0, v0
	s_and_saveexec_b64 s[30:31], vcc
	s_cbranch_execz .LBB0_471
	s_lshl_b64 s[34:35], s[6:7], 2
	s_add_u32 s34, s56, s34
	s_addc_u32 s35, s57, s35
	s_bcnt1_i32_b64 s7, s[8:9]
	v_mov_b32_e32 v1, s7
	global_atomic_add v1, v131, v1, s[34:35] offset:32 sc0
